# pool_unit scan loop: the eight LDS reads of each 4-step trip issued together at its top with counted lgkmcnt hand-over (was read-wait-use per value)
# speedup vs baseline: 1.0039x; 1.0039x over previous
.LBB0_1002:
	v_add_u32_e32 v28, v6, v3
	ds_read_u16 v20, v6
	ds_read_u16 v21, v28
	ds_read_u16 v22, v6 offset:1024
	ds_read_u16 v23, v28 offset:1024
	ds_read_u16 v24, v6 offset:2048
	ds_read_u16 v25, v28 offset:2048
	ds_read_u16 v26, v28 offset:3072
	ds_read_u16 v27, v6 offset:3072
	s_add_i32 s0, s2, s3
	s_add_i32 s1, s0, 1
	s_add_i32 s3, s3, 4
	s_waitcnt lgkmcnt(7)
	v_mov_b32_e32 v4, v20
	v_lshlrev_b32_e32 v4, 16, v4
	v_add_f32_e32 v5, v7, v4
	v_add_u32_e32 v7, v6, v3
	s_waitcnt lgkmcnt(6)
	v_mov_b32_e32 v8, v21
	v_lshlrev_b32_e32 v8, 16, v8
	v_sub_f32_e32 v5, v5, v8
	v_min_i32_e32 v8, s1, v2
	v_cvt_f32_i32_e32 v8, v8
	s_add_i32 s1, s0, 2
	v_div_scale_f32 v9, s[4:5], v8, v8, v5
	v_rcp_f32_e32 v10, v9
	s_nop 0
	v_fma_f32 v11, -v9, v10, 1.0
	v_fmac_f32_e32 v10, v11, v10
	v_div_scale_f32 v11, vcc, v5, v8, v5
	v_mul_f32_e32 v12, v11, v10
	v_fma_f32 v13, -v9, v12, v11
	v_fmac_f32_e32 v12, v13, v10
	v_fma_f32 v9, -v9, v12, v11
	v_div_fmas_f32 v9, v9, v10, v12
	v_div_fixup_f32 v8, v9, v8, v5
	v_sub_f32_e32 v4, v8, v4
	v_cvt_pk_bf16_f32 v4, v4, 0
	global_store_short v[0:1], v4, off offset:-2048
	s_waitcnt lgkmcnt(5)
	v_mov_b32_e32 v4, v22
	v_lshlrev_b32_e32 v4, 16, v4
	v_add_f32_e32 v5, v5, v4
	s_waitcnt lgkmcnt(4)
	v_mov_b32_e32 v8, v23
	v_lshlrev_b32_e32 v8, 16, v8
	v_sub_f32_e32 v5, v5, v8
	v_min_i32_e32 v8, s1, v2
	v_cvt_f32_i32_e32 v8, v8
	s_add_i32 s1, s0, 3
	s_add_i32 s0, s0, 4
	s_cmp_lg_u32 s3, 64
	v_div_scale_f32 v9, s[4:5], v8, v8, v5
	v_rcp_f32_e32 v10, v9
	s_nop 0
	v_fma_f32 v11, -v9, v10, 1.0
	v_fmac_f32_e32 v10, v11, v10
	v_div_scale_f32 v11, vcc, v5, v8, v5
	v_mul_f32_e32 v12, v11, v10
	v_fma_f32 v13, -v9, v12, v11
	v_fmac_f32_e32 v12, v13, v10
	v_fma_f32 v9, -v9, v12, v11
	v_div_fmas_f32 v9, v9, v10, v12
	v_div_fixup_f32 v8, v9, v8, v5
	v_sub_f32_e32 v4, v8, v4
	v_cvt_pk_bf16_f32 v4, v4, 0
	global_store_short v[0:1], v4, off offset:-1024
	s_waitcnt lgkmcnt(3)
	v_mov_b32_e32 v4, v24
	v_lshlrev_b32_e32 v4, 16, v4
	v_add_f32_e32 v5, v5, v4
	s_waitcnt lgkmcnt(2)
	v_mov_b32_e32 v8, v25
	v_lshlrev_b32_e32 v8, 16, v8
	v_sub_f32_e32 v5, v5, v8
	v_min_i32_e32 v8, s1, v2
	v_cvt_f32_i32_e32 v8, v8
	s_waitcnt lgkmcnt(1)
	v_mov_b32_e32 v7, v26
	v_lshlrev_b32_e32 v7, 16, v7
	v_div_scale_f32 v9, s[4:5], v8, v8, v5
	v_rcp_f32_e32 v10, v9
	s_nop 0
	v_fma_f32 v11, -v9, v10, 1.0
	v_fmac_f32_e32 v10, v11, v10
	v_div_scale_f32 v11, vcc, v5, v8, v5
	v_mul_f32_e32 v12, v11, v10
	v_fma_f32 v13, -v9, v12, v11
	v_fmac_f32_e32 v12, v13, v10
	v_fma_f32 v9, -v9, v12, v11
	v_div_fmas_f32 v9, v9, v10, v12
	v_div_fixup_f32 v8, v9, v8, v5
	v_sub_f32_e32 v4, v8, v4
	v_cvt_pk_bf16_f32 v4, v4, 0
	global_store_short v[0:1], v4, off
	v_add_u32_e32 v6, 0x1000, v6
	s_waitcnt lgkmcnt(0)
	v_mov_b32_e32 v4, v27
	v_lshlrev_b32_e32 v4, 16, v4
	v_add_f32_e32 v5, v5, v4
	v_sub_f32_e32 v7, v5, v7
	v_min_i32_e32 v5, s0, v2
	v_cvt_f32_i32_e32 v5, v5
	v_div_scale_f32 v8, s[0:1], v5, v5, v7
	v_rcp_f32_e32 v9, v8
	s_mov_b64 s[0:1], 0x1000
	v_fma_f32 v10, -v8, v9, 1.0
	v_fmac_f32_e32 v9, v10, v9
	v_div_scale_f32 v10, vcc, v7, v5, v7
	v_mul_f32_e32 v11, v10, v9
	v_fma_f32 v12, -v8, v11, v10
	v_fmac_f32_e32 v11, v12, v9
	v_fma_f32 v8, -v8, v11, v10
	v_div_fmas_f32 v8, v8, v9, v11
	v_div_fixup_f32 v5, v8, v5, v7
	v_sub_f32_e32 v4, v5, v4
	v_cvt_pk_bf16_f32 v4, v4, 0
	global_store_short v[0:1], v4, off offset:1024
	v_lshl_add_u64 v[0:1], v[0:1], 0, s[0:1]
	s_cbranch_scc1 .LBB0_1002
	v_readlane_b32 s0, v253, 7
	s_add_i32 s13, s13, s59
	s_add_i32 s12, s12, s0
	s_cmpk_gt_i32 s13, 0x1ff
	s_cbranch_scc0 .LBB0_990
